# seam-1 arrive: only the L2 write-back at the arrive, the counter increment deferred behind the next GEMM unit's prologue DMA wait (overlaps write-back latency with DMA latency)
# baseline (speedup 1.0000x reference)
; #define LAS __attribute__((address_space(3)))
; template <class Epi, class Sched, bool ALIGN_EPI = false, bool SP2 = false>
; __device__ __forceinline__ void gemm_phase(PG8_LAS unsigned char* lds, const Gemm g, const Sched& S, const Epi& E) {
;     const int tid = threadIdx.x, wid = __builtin_amdgcn_readfirstlane(tid >> 6), lane = tid & 63, wr = wid >> 2, wc = wid & 3, fr = lane & 15, fq = lane >> 4;
;     const int K = g.K, nt = K / BK;
;     unsigned voffA[2], voffB[2];
; #pragma unroll
;     for (int i = 0; i < 2; ++i) { int R, C; stage_rc(tid * 16 + i * 8192, R, C); const int Rb = Epi::PERM ? ((R & ~31) + perm32(R & 31)) : R;
;         voffA[i] = (unsigned)(R * K + C) * 2u; voffB[i] = (unsigned)(Rb * K + C) * 2u; }
;     const size_t kstep = (size_t)(BK * 2);
;     const size_t hstep = (size_t)HALF * K * 2;
;     const size_t tstep = 2 * hstep;
;     const unsigned ldsw = (unsigned)wid * 1024u;
;     const int aoff = lds_byte(wr * 64 + fr, fq * 8), boff = lds_byte(wc * 32 + fr, fq * 8);
; __global__ void __launch_bounds__(NWAVES * 64, 2) mega_fwd(Args a) {
;     ...
;     if (IN(1)) {
;         pg8::Gemm g{XN, Win_t, M, PW, DM}; pg8::StaticOrder S; S.init(M, PW, G, bx);
;         pg8::EpiInProj E{PostP{a.qna, a.kna, a.qnb, a.knb, a.pos, INV_FREQ, QA, KA, VA, GA, QB, KB, VB, GB}};
;         for (int part = 0; part < 2; ++part) {
;             pg8::RangeOrder R{S, 0, 1 << 30};
;             if (split7) { if (part == 0) { R.lo = 0; R.hi = 6; } else { R.lo = 6; R.hi = 7; } } else if (part == 1) break;
;             if (part == 1 && bx >= 64) break;
;             pg8::gemm_phase<pg8::EpiInProj, pg8::RangeOrder, true, true>((LAS unsigned char*)lds, g, R, E);
.LBB0_61:
	s_mov_b64 s[100:101], 0
	s_cmp_lt_i32 s78, 2
	s_cselect_b64 s[2:3], -1, 0
	s_add_u32 s80, s76, 0x3000000
	s_addc_u32 s81, s77, 0
	s_add_u32 s74, s76, 0x7000000
	s_addc_u32 s75, s77, 0
	s_add_u32 s4, s76, 0x9000000
	v_writelane_b32 v254, s4, 16
	s_addc_u32 s4, s77, 0
	v_writelane_b32 v254, s4, 17
	s_add_u32 s4, s76, 0xb000000
	v_writelane_b32 v254, s4, 18
	s_addc_u32 s4, s77, 0
	v_writelane_b32 v254, s4, 19
	s_add_u32 s4, s76, 0xd000000
	v_writelane_b32 v254, s4, 20
	s_addc_u32 s4, s77, 0
	s_waitcnt lgkmcnt(0)
	s_add_u32 s68, s76, 0xf000000
	s_addc_u32 s69, s77, 0
	v_writelane_b32 v254, s4, 21
	s_add_u32 s4, s76, 0x2800000
	v_writelane_b32 v254, s4, 22
	s_addc_u32 s4, s77, 0
	v_writelane_b32 v254, s4, 23
	s_add_u32 s4, s76, 0x2c00000
	v_writelane_b32 v254, s4, 24
	s_addc_u32 s4, s77, 0
	v_writelane_b32 v254, s4, 25
	s_add_u32 s4, s76, 0x11000000
	v_writelane_b32 v254, s4, 26
	s_addc_u32 s4, s77, 0
	s_cmpk_eq_i32 s83, 0x100
	v_writelane_b32 v254, s4, 27
	s_cselect_b64 s[4:5], -1, 0
	v_writelane_b32 v254, s4, 28
	s_mov_b64 s[12:13], s[56:57]
	s_mov_b64 s[14:15], s[58:59]
	v_writelane_b32 v254, s5, 29
	s_mov_b64 s[16:17], s[60:61]
	s_mov_b64 s[18:19], s[62:63]
	s_mov_b64 s[20:21], s[64:65]
	s_mov_b64 s[22:23], s[66:67]
	s_mov_b64 s[26:27], s[70:71]
	v_writelane_b32 v254, s12, 30
	s_cmpk_lg_i32 s83, 0x100
	s_cselect_b64 s[28:29], -1, 0
	v_writelane_b32 v254, s13, 31
	v_writelane_b32 v254, s14, 32
	v_writelane_b32 v254, s15, 33
	v_writelane_b32 v254, s16, 34
	v_writelane_b32 v254, s17, 35
	v_writelane_b32 v254, s18, 36
	v_writelane_b32 v254, s19, 37
	v_writelane_b32 v254, s20, 38
	v_writelane_b32 v254, s21, 39
	v_writelane_b32 v254, s22, 40
	v_writelane_b32 v254, s23, 41
	v_writelane_b32 v254, s24, 42
	v_writelane_b32 v254, s25, 43
	v_writelane_b32 v254, s26, 44
	v_writelane_b32 v254, s27, 45
	v_writelane_b32 v254, s68, 46
	v_writelane_b32 v254, s69, 47
	s_and_b64 s[8:9], s[2:3], s[0:1]
	v_writelane_b32 v254, s28, 48
	s_andn2_b64 vcc, exec, s[8:9]
	v_cmp_eq_u32_e64 s[0:1], 0, v229
	v_mbcnt_lo_u32_b32 v145, -1, 0
	v_writelane_b32 v254, s29, 49
	s_cbranch_vccnz .LBB0_167
	s_waitcnt vmcnt(7)
	v_lshrrev_b32_e32 v5, 5, v229
	s_waitcnt vmcnt(6)
	v_lshrrev_b32_e32 v7, 1, v229
	v_and_b32_e32 v5, 4, v5
	v_bfe_u32 v6, v229, 2, 2
	v_and_b32_e32 v144, 24, v7
	v_lshlrev_b32_e32 v0, 4, v229
	v_and_b32_e32 v1, 32, v229
	v_bfe_u32 v2, v229, 2, 4
	v_or3_b32 v5, v5, v6, v144
	v_lshrrev_b32_e32 v6, 3, v229
	s_movk_i32 s2, 0x70
	v_bitop3_b32 v3, v0, v1, 48 bitop3:0x6c
	v_and_b32_e32 v4, 64, v229
	v_and_or_b32 v7, v6, s2, v2
	s_movk_i32 s2, 0x60
	v_or_b32_e32 v1, v3, v4
	v_and_or_b32 v6, v6, s2, v5
	v_lshl_or_b32 v148, v6, 12, v1
	v_add_u32_e32 v6, 0x2000, v0
	s_cmp_gt_i32 s82, 63
	v_lshrrev_b32_e32 v0, 7, v6
	s_movk_i32 s2, 0xf0
	s_cselect_b64 s[10:11], -1, 0
	v_lshl_or_b32 v146, v7, 12, v1
	v_and_or_b32 v7, v0, s2, v2
	s_movk_i32 s2, 0xe0
	s_ashr_i32 s33, s83, 31
	s_ashr_i32 s50, s82, 31
	v_and_or_b32 v0, v0, s2, v5
	s_getpc_b64 s[2:3]
	s_add_u32 s2, s2, _ZL8INV_FREQ@rel32@lo+4
	s_addc_u32 s3, s3, _ZL8INV_FREQ@rel32@hi+12
	s_mul_i32 s4, s83, 6
	s_mul_hi_i32 s5, s83, 6
	s_add_u32 s4, s4, s82
	s_addc_u32 s5, s5, s50
	s_ashr_i32 s12, s4, 31
	s_lshr_b32 s12, s12, 29
	s_add_i32 s12, s4, s12
	s_ashr_i32 s13, s12, 3
	s_and_b32 s12, s12, -8
	s_sub_i32 s12, s4, s12
	s_cmp_lt_i32 s12, 0
	s_movk_i32 s51, 0xc9
	s_cselect_b32 s14, s51, 0xc8
	s_mul_i32 s12, s12, s14
	s_add_i32 s12, s12, s13
	s_mul_hi_i32 s13, s12, 0x51eb851f
	s_lshr_b32 s14, s13, 31
	s_ashr_i32 s13, s13, 6
	s_add_i32 s14, s13, s14
	s_lshl_b32 s52, s14, 3
	s_sub_i32 s13, 64, s52
	s_min_i32 s13, s13, 8
	s_abs_i32 s15, s13
	v_lshl_or_b32 v150, v7, 12, v1
	v_cvt_f32_u32_e32 v7, s15
	v_lshl_or_b32 v152, v0, 12, v1
	v_lshlrev_b32_e32 v0, 6, v229
	v_lshlrev_b32_e32 v1, 2, v229
	v_lshlrev_b32_e32 v5, 1, v144
	v_and_b32_e32 v0, 0x3c0, v0
	v_and_b32_e32 v1, 32, v1
	v_bitop3_b32 v177, v5, v1, v0 bitop3:0x36
	v_mov_b32_e32 v155, 0
	v_lshlrev_b32_e32 v154, 2, v144
	v_mov_b64_e32 v[0:1], 0x640
	v_lshl_add_u64 v[156:157], s[2:3], 0, v[154:155]
	v_cmp_lt_i64_e64 s[2:3], s[4:5], v[0:1]
	v_rcp_iflag_f32_e32 v0, v7
	s_mulk_i32 s14, 0xc8
	s_sub_i32 s4, s12, s14
	s_sub_i32 s12, 0, s15
	v_mul_f32_e32 v0, 0x4f7ffffe, v0
	v_cvt_u32_f32_e32 v0, v0
	s_ashr_i32 s5, s4, 31
	s_abs_i32 s4, s4
	v_lshlrev_b32_e32 v1, 12, v2
	v_readfirstlane_b32 s14, v0
	s_mul_i32 s12, s12, s14
	s_mul_hi_u32 s12, s14, s12
	s_add_i32 s14, s14, s12
	s_mul_hi_u32 s12, s4, s14
	s_mul_i32 s12, s12, s15
	s_sub_i32 s4, s4, s12
	s_sub_i32 s12, s4, s15
	s_cmp_ge_u32 s4, s15
	s_cselect_b32 s4, s12, s4
	s_sub_i32 s12, s4, s15
	s_cmp_ge_u32 s4, s15
	s_cselect_b32 s4, s12, s4
	s_xor_b32 s4, s4, s5
	s_sub_i32 s4, s4, s5
	s_add_i32 s52, s52, s4
	v_lshlrev_b32_e32 v0, 9, v229
	s_mov_b32 s4, 0x70000
	v_and_or_b32 v0, v0, s4, v3
	v_or3_b32 v158, v0, v1, v4
	v_lshlrev_b32_e32 v0, 5, v6
	s_mov_b32 s4, 0xf0000
	v_and_b32_e32 v176, 15, v229
	v_and_or_b32 v0, v0, s4, v3
	v_or3_b32 v160, v0, v1, v4
	v_lshlrev_b32_e32 v0, 2, v176
	v_mov_b32_e32 v149, v155
	v_mov_b32_e32 v153, v155
	v_mov_b32_e32 v147, v155
	v_mov_b32_e32 v151, v155
	s_mov_b32 s13, 0
	v_mov_b32_e32 v159, v155
	v_mov_b32_e32 v161, v155
	s_mov_b64 s[16:17], -1
	s_mov_b64 s[18:19], 0
	v_lshl_or_b32 v178, v176, 6, v5
	v_and_b32_e32 v179, 32, v0
	s_mov_b64 s[14:15], 0x80
	v_mov_b32_e32 v180, 0x358637bd
	s_mov_b32 s53, 0x800000
	v_mov_b32_e32 v181, 1
	v_mov_b64_e32 v[162:163], 0x63f
	v_mbcnt_hi_u32_b32 v182, -1, v145
	s_branch .LBB0_66

; __global__ void __launch_bounds__(NWAVES * 64, 2) mega_fwd(Args a) {
;     ...
;         for (int part = 0; part < 2; ++part) {
;             pg8::RangeOrder R{S, 0, 1 << 30};
;             if (split7) { if (part == 0) { R.lo = 0; R.hi = 6; } else { R.lo = 6; R.hi = 7; } } else if (part == 1) break;
;             if (part == 1 && bx >= 64) break;
.LBB0_68:
	s_andn2_b64 vcc, exec, s[20:21]
	s_cbranch_vccnz .LBB0_70
	s_and_b64 s[4:5], s[10:11], exec
	s_cselect_b32 s32, 6, 7
	s_and_b64 s[4:5], s[16:17], exec
	s_cselect_b32 s55, 0, 5
	s_cselect_b32 s56, 5, s32
	s_mov_b64 s[4:5], -1
	s_branch .LBB0_71

; #define PG8_STAGE(bufoff, gbase, voff) do { _Pragma("unroll") for (int _i = 0; _i < 2; ++_i) \
;         __builtin_amdgcn_global_load_lds((const unsigned*)((const char*)(gbase) + (voff)[_i]), (PG8_LAS unsigned*)(lds + (bufoff) + ldsw + _i * 8192), 16, 0, 0); } while (0)
; #define PG8_WAIT_V(n) asm volatile("s_waitcnt vmcnt(" #n ")" ::: "memory")
; #define PG8_BAR __builtin_amdgcn_s_barrier()
; template <class Epi, class Sched, bool ALIGN_EPI = false, bool SP2 = false>
; __device__ __forceinline__ void gemm_phase(PG8_LAS unsigned char* lds, const Gemm g, const Sched& S, const Epi& E) {
;     ...
;         PG8_STAGE(PG8_SB(1, 0), cB + kstep, voffB); PG8_STAGE(PG8_SA(1, 0), cA + kstep, voffA); PG8_STAGE(PG8_SB(1, 1), cB + hstep + kstep, voffB);
;         PG8_WAIT_V(6); PG8_BAR;
; __device__ __forceinline__ void bar_arrive(unsigned* ctr) {
;     asm volatile("s_waitcnt vmcnt(0)" ::: "memory");
;     __syncthreads();
;     if (threadIdx.x == 0) { __builtin_amdgcn_fence(__ATOMIC_RELEASE, "agent"); asm volatile("s_waitcnt vmcnt(0)" ::: "memory"); __hip_atomic_fetch_add(ctr, 1u, __ATOMIC_RELAXED, __HIP_MEMORY_SCOPE_AGENT); }
; }
.LBB0_78:
	s_add_i32 m0, s58, 0x18000
	v_lshl_add_u64 v[0:1], v[0:1], 0, s[14:15]
	s_and_b32 s62, s21, 3
	s_lshl_b32 s5, s20, 13
	s_waitcnt vmcnt(2)
	s_barrier
	global_load_lds_dwordx4 v[0:1], off
	v_lshl_add_u64 v[0:1], v[2:3], 0, s[14:15]
	s_add_i32 m0, s58, 0x1a000
	s_add_i32 s63, s58, 0x8000
	s_add_i32 s64, s58, 0xa000
	global_load_lds_dwordx4 v[0:1], off
	v_lshl_add_u64 v[0:1], v[6:7], 0, s[14:15]
	s_mov_b32 m0, s63
	s_add_u32 s22, s40, 0x80080
	global_load_lds_dwordx4 v[0:1], off
	v_lshl_add_u64 v[0:1], v[4:5], 0, s[14:15]
	s_mov_b32 m0, s64
	s_addc_u32 s23, s41, 0
	global_load_lds_dwordx4 v[0:1], off
	s_add_i32 m0, s58, 0x1c000
	v_lshl_add_u64 v[0:1], s[22:23], 0, v[148:149]
	global_load_lds_dwordx4 v[0:1], off
	v_lshl_add_u64 v[0:1], s[22:23], 0, v[152:153]
	s_add_i32 m0, s58, 0x1e000
	s_cmpk_lt_u32 s12, 0x100
	global_load_lds_dwordx4 v[0:1], off
	s_waitcnt vmcnt(6)
	s_mov_b64 exec, s[100:101]
	s_cbranch_execz .Lda_skip
	global_atomic_add v155, v181, s[76:77]
	s_mov_b64 s[100:101], 0
.Lda_skip:
	s_mov_b64 exec, -1
	v_bitop3_b32 v0, v178, s5, v179 bitop3:0xde
	v_lshl_or_b32 v183, s20, 6, v176
	v_lshl_or_b32 v184, s62, 12, v177
	s_mov_b32 s65, 0
	s_cselect_b64 s[20:21], -1, 0
	v_add_u32_e32 v185, 0, v0
	v_readlane_b32 s66, v254, 16
	v_readlane_b32 s67, v254, 17
	s_barrier
	s_branch .LBB0_81

; __device__ __forceinline__ void bar_arrive(unsigned* ctr) {
;     asm volatile("s_waitcnt vmcnt(0)" ::: "memory");
;     __syncthreads();
;     if (threadIdx.x == 0) { __builtin_amdgcn_fence(__ATOMIC_RELEASE, "agent"); asm volatile("s_waitcnt vmcnt(0)" ::: "memory"); __hip_atomic_fetch_add(ctr, 1u, __ATOMIC_RELAXED, __HIP_MEMORY_SCOPE_AGENT); }
; }
.LBB0_163:
	s_and_b64 vcc, exec, s[18:19]
	s_cbranch_vccz .LBB0_64
	s_waitcnt vmcnt(0)
	s_waitcnt vmcnt(0)
	s_barrier
	s_and_saveexec_b64 s[16:17], s[0:1]
	s_cbranch_execz .LBB0_63
	buffer_wbl2 sc1
	s_mov_b64 s[100:101], exec
	s_branch .LBB0_63
